# combo6 + pool thin phase: the four row-block chunks of a column block are requested together with the halo chunk (one memory round trip per column block instead of five)
# speedup vs baseline: 1.0085x; 1.0085x over previous
; #define LAS __attribute__((address_space(3)))
; #define GAS __attribute__((address_space(1)))
; template <int W>
; __device__ __forceinline__ void pool_cols(LAS float* scr, const LAS float* rl, const bf16_t* XAi, bf16_t* PA, int r0, int tseq0, int wave, int lane) {
;     int rr, q; pg8::subtile_lane(lane, rr, q);
;     for (int j = 0; j < 8; ++j) {
;         const int q8 = (wave * 8 + j) * 4 + q;
;         u32x4 nx = {0u, 0u, 0u, 0u};
;         if (tseq0 != 0) nx = *(const GAS u32x4*)((const GAS char*)XAi + pg8::img_chunk(r0 - 16 + rr, q8, KT_D));
; #pragma unroll 1
;         for (int rb = -1; rb < 4; ++rb) {
;             const int row = r0 + rb * 16 + rr;
;             const u32x4 xx = nx;
;             if (rb < 3) nx = *(const GAS u32x4*)((const GAS char*)XAi + pg8::img_chunk(row + 16, q8, KT_D));
;             float v[8];
.LBB0_465:
	s_add_u32 s84, s58, s88
	s_addc_u32 s85, s59, s89
	v_add_u32_e32 v45, 0, v38
	v_add_u32_e32 v44, 0x0, v39
	v_ashrrev_i32_e32 v2, 7, v45
	v_lshrrev_b32_e32 v4, 3, v45
	v_ashrrev_i32_e32 v3, 31, v2
	v_and_or_b32 v4, v4, 14, s46
	v_lshrrev_b32_e32 v5, 4, v44
	v_and_or_b32 v0, v44, s33, v19
	v_lshlrev_b64 v[2:3], 19, v[2:3]
	v_lshlrev_b32_e32 v4, 10, v4
	v_and_b32_e32 v5, 32, v5
	v_bitop3_b32 v0, v4, v0, v5 bitop3:0xf6
	v_lshl_add_u64 v[2:3], s[84:85], 0, v[2:3]
	v_lshl_add_u64 v[2:3], v[2:3], 0, v[0:1]
	global_load_dwordx4 v[64:67], v[2:3], off
	v_add_u32_e32 v45, 16, v38
	v_add_u32_e32 v44, 0x400, v39
	v_ashrrev_i32_e32 v2, 7, v45
	v_lshrrev_b32_e32 v4, 3, v45
	v_ashrrev_i32_e32 v3, 31, v2
	v_and_or_b32 v4, v4, 14, s46
	v_lshrrev_b32_e32 v5, 4, v44
	v_and_or_b32 v0, v44, s33, v19
	v_lshlrev_b64 v[2:3], 19, v[2:3]
	v_lshlrev_b32_e32 v4, 10, v4
	v_and_b32_e32 v5, 32, v5
	v_bitop3_b32 v0, v4, v0, v5 bitop3:0xf6
	v_lshl_add_u64 v[2:3], s[84:85], 0, v[2:3]
	v_lshl_add_u64 v[2:3], v[2:3], 0, v[0:1]
	global_load_dwordx4 v[68:71], v[2:3], off
	v_add_u32_e32 v45, 32, v38
	v_add_u32_e32 v44, 0x800, v39
	v_ashrrev_i32_e32 v2, 7, v45
	v_lshrrev_b32_e32 v4, 3, v45
	v_ashrrev_i32_e32 v3, 31, v2
	v_and_or_b32 v4, v4, 14, s46
	v_lshrrev_b32_e32 v5, 4, v44
	v_and_or_b32 v0, v44, s33, v19
	v_lshlrev_b64 v[2:3], 19, v[2:3]
	v_lshlrev_b32_e32 v4, 10, v4
	v_and_b32_e32 v5, 32, v5
	v_bitop3_b32 v0, v4, v0, v5 bitop3:0xf6
	v_lshl_add_u64 v[2:3], s[84:85], 0, v[2:3]
	v_lshl_add_u64 v[2:3], v[2:3], 0, v[0:1]
	global_load_dwordx4 v[72:75], v[2:3], off
	v_add_u32_e32 v45, 48, v38
	v_add_u32_e32 v44, 0xc00, v39
	v_ashrrev_i32_e32 v2, 7, v45
	v_lshrrev_b32_e32 v4, 3, v45
	v_ashrrev_i32_e32 v3, 31, v2
	v_and_or_b32 v4, v4, 14, s46
	v_lshrrev_b32_e32 v5, 4, v44
	v_and_or_b32 v0, v44, s33, v19
	v_lshlrev_b64 v[2:3], 19, v[2:3]
	v_lshlrev_b32_e32 v4, 10, v4
	v_and_b32_e32 v5, 32, v5
	v_bitop3_b32 v0, v4, v0, v5 bitop3:0xf6
	v_lshl_add_u64 v[2:3], s[84:85], 0, v[2:3]
	v_lshl_add_u64 v[2:3], v[2:3], 0, v[0:1]
	global_load_dwordx4 v[76:79], v[2:3], off
	s_add_u32 s88, s86, s88
	s_waitcnt vmcnt(0)
	v_mov_b64_e32 v[2:3], v[10:11]
	s_addc_u32 s89, s87, s89
	s_mov_b32 s69, -1
	s_mov_b32 s68, 0
	v_mov_b32_e32 v43, v36
	s_mov_b32 s90, 0
	v_mov_b64_e32 v[4:5], v[12:13]
	s_branch .LBB0_467
.LBB0_466:
	s_add_i32 s90, s90, 16
	s_addk_i32 s68, 0x400
	s_add_i32 s69, s69, 1
	v_mov_b64_e32 v[12:13], v[4:5]
	v_add_u32_e32 v43, 64, v43
	s_cmpk_eq_i32 s90, 0x50
	v_mov_b64_e32 v[10:11], v[2:3]
	s_cbranch_scc1 .LBB0_461
.LBB0_467:
	v_add_u32_e32 v45, s90, v38
	s_cmp_eq_u32 s90, 64
	v_add_u32_e32 v44, s68, v39
	s_cbranch_scc1 .LBB0_469
	s_cmp_lg_u32 s90, 0
	s_cbranch_scc1 .Lpool_sel_0_1
	v_mov_b32_e32 v2, v64
	v_mov_b32_e32 v3, v65
	v_mov_b32_e32 v4, v66
	v_mov_b32_e32 v5, v67
	s_branch .LBB0_469
.Lpool_sel_0_1:
	s_cmp_lg_u32 s90, 16
	s_cbranch_scc1 .Lpool_sel_0_2
	v_mov_b32_e32 v2, v68
	v_mov_b32_e32 v3, v69
	v_mov_b32_e32 v4, v70
	v_mov_b32_e32 v5, v71
	s_branch .LBB0_469
.Lpool_sel_0_2:
	s_cmp_lg_u32 s90, 32
	s_cbranch_scc1 .Lpool_sel_0_3
	v_mov_b32_e32 v2, v72
	v_mov_b32_e32 v3, v73
	v_mov_b32_e32 v4, v74
	v_mov_b32_e32 v5, v75
	s_branch .LBB0_469
.Lpool_sel_0_3:
	v_mov_b32_e32 v2, v76
	v_mov_b32_e32 v3, v77
	v_mov_b32_e32 v4, v78
	v_mov_b32_e32 v5, v79

; #define LAS __attribute__((address_space(3)))
; #define GAS __attribute__((address_space(1)))
; template <int W>
; __device__ __forceinline__ void pool_cols(LAS float* scr, const LAS float* rl, const bf16_t* XAi, bf16_t* PA, int r0, int tseq0, int wave, int lane) {
;     int rr, q; pg8::subtile_lane(lane, rr, q);
;     for (int j = 0; j < 8; ++j) {
;         const int q8 = (wave * 8 + j) * 4 + q;
;         u32x4 nx = {0u, 0u, 0u, 0u};
;         if (tseq0 != 0) nx = *(const GAS u32x4*)((const GAS char*)XAi + pg8::img_chunk(r0 - 16 + rr, q8, KT_D));
; #pragma unroll 1
;         for (int rb = -1; rb < 4; ++rb) {
;             const int row = r0 + rb * 16 + rr;
;             const u32x4 xx = nx;
;             if (rb < 3) nx = *(const GAS u32x4*)((const GAS char*)XAi + pg8::img_chunk(row + 16, q8, KT_D));
;             float v[8];
.LBB0_479:
	s_add_u32 s40, s58, s84
	s_addc_u32 s41, s59, s85
	v_add_u32_e32 v45, 0, v38
	v_add_u32_e32 v44, 0x0, v39
	v_ashrrev_i32_e32 v2, 7, v45
	v_lshrrev_b32_e32 v4, 3, v45
	v_ashrrev_i32_e32 v3, 31, v2
	v_and_or_b32 v4, v4, 14, s46
	v_lshrrev_b32_e32 v5, 4, v44
	v_and_or_b32 v0, v44, s33, v19
	v_lshlrev_b64 v[2:3], 19, v[2:3]
	v_lshlrev_b32_e32 v4, 10, v4
	v_and_b32_e32 v5, 32, v5
	v_bitop3_b32 v0, v4, v0, v5 bitop3:0xf6
	v_lshl_add_u64 v[2:3], s[40:41], 0, v[2:3]
	v_lshl_add_u64 v[2:3], v[2:3], 0, v[0:1]
	global_load_dwordx4 v[64:67], v[2:3], off
	v_add_u32_e32 v45, 16, v38
	v_add_u32_e32 v44, 0x400, v39
	v_ashrrev_i32_e32 v2, 7, v45
	v_lshrrev_b32_e32 v4, 3, v45
	v_ashrrev_i32_e32 v3, 31, v2
	v_and_or_b32 v4, v4, 14, s46
	v_lshrrev_b32_e32 v5, 4, v44
	v_and_or_b32 v0, v44, s33, v19
	v_lshlrev_b64 v[2:3], 19, v[2:3]
	v_lshlrev_b32_e32 v4, 10, v4
	v_and_b32_e32 v5, 32, v5
	v_bitop3_b32 v0, v4, v0, v5 bitop3:0xf6
	v_lshl_add_u64 v[2:3], s[40:41], 0, v[2:3]
	v_lshl_add_u64 v[2:3], v[2:3], 0, v[0:1]
	global_load_dwordx4 v[68:71], v[2:3], off
	v_add_u32_e32 v45, 32, v38
	v_add_u32_e32 v44, 0x800, v39
	v_ashrrev_i32_e32 v2, 7, v45
	v_lshrrev_b32_e32 v4, 3, v45
	v_ashrrev_i32_e32 v3, 31, v2
	v_and_or_b32 v4, v4, 14, s46
	v_lshrrev_b32_e32 v5, 4, v44
	v_and_or_b32 v0, v44, s33, v19
	v_lshlrev_b64 v[2:3], 19, v[2:3]
	v_lshlrev_b32_e32 v4, 10, v4
	v_and_b32_e32 v5, 32, v5
	v_bitop3_b32 v0, v4, v0, v5 bitop3:0xf6
	v_lshl_add_u64 v[2:3], s[40:41], 0, v[2:3]
	v_lshl_add_u64 v[2:3], v[2:3], 0, v[0:1]
	global_load_dwordx4 v[72:75], v[2:3], off
	v_add_u32_e32 v45, 48, v38
	v_add_u32_e32 v44, 0xc00, v39
	v_ashrrev_i32_e32 v2, 7, v45
	v_lshrrev_b32_e32 v4, 3, v45
	v_ashrrev_i32_e32 v3, 31, v2
	v_and_or_b32 v4, v4, 14, s46
	v_lshrrev_b32_e32 v5, 4, v44
	v_and_or_b32 v0, v44, s33, v19
	v_lshlrev_b64 v[2:3], 19, v[2:3]
	v_lshlrev_b32_e32 v4, 10, v4
	v_and_b32_e32 v5, 32, v5
	v_bitop3_b32 v0, v4, v0, v5 bitop3:0xf6
	v_lshl_add_u64 v[2:3], s[40:41], 0, v[2:3]
	v_lshl_add_u64 v[2:3], v[2:3], 0, v[0:1]
	global_load_dwordx4 v[76:79], v[2:3], off
	s_add_u32 s84, s86, s84
	s_waitcnt vmcnt(0)
	v_mov_b64_e32 v[2:3], v[10:11]
	s_addc_u32 s85, s87, s85
	s_mov_b32 s69, -1
	s_mov_b32 s88, 0
	v_mov_b32_e32 v43, v36
	s_mov_b32 s89, 0
	v_mov_b64_e32 v[4:5], v[12:13]
	s_branch .LBB0_481
.LBB0_480:
	s_add_i32 s89, s89, 16
	s_addk_i32 s88, 0x400
	s_add_i32 s69, s69, 1
	v_mov_b64_e32 v[12:13], v[4:5]
	v_add_u32_e32 v43, 64, v43
	s_cmpk_eq_i32 s89, 0x50
	v_mov_b64_e32 v[10:11], v[2:3]
	s_cbranch_scc1 .LBB0_475
.LBB0_481:
	v_add_u32_e32 v45, s89, v38
	s_cmp_eq_u32 s89, 64
	v_add_u32_e32 v44, s88, v39
	s_cbranch_scc1 .LBB0_483
	s_cmp_lg_u32 s89, 0
	s_cbranch_scc1 .Lpool_sel_1_1
	v_mov_b32_e32 v2, v64
	v_mov_b32_e32 v3, v65
	v_mov_b32_e32 v4, v66
	v_mov_b32_e32 v5, v67
	s_branch .LBB0_483
.Lpool_sel_1_1:
	s_cmp_lg_u32 s89, 16
	s_cbranch_scc1 .Lpool_sel_1_2
	v_mov_b32_e32 v2, v68
	v_mov_b32_e32 v3, v69
	v_mov_b32_e32 v4, v70
	v_mov_b32_e32 v5, v71
	s_branch .LBB0_483
.Lpool_sel_1_2:
	s_cmp_lg_u32 s89, 32
	s_cbranch_scc1 .Lpool_sel_1_3
	v_mov_b32_e32 v2, v72
	v_mov_b32_e32 v3, v73
	v_mov_b32_e32 v4, v74
	v_mov_b32_e32 v5, v75
	s_branch .LBB0_483

; #define LAS __attribute__((address_space(3)))
; #define GAS __attribute__((address_space(1)))
; template <int W>
; __device__ __forceinline__ void pool_cols(LAS float* scr, const LAS float* rl, const bf16_t* XAi, bf16_t* PA, int r0, int tseq0, int wave, int lane) {
;     int rr, q; pg8::subtile_lane(lane, rr, q);
;     for (int j = 0; j < 8; ++j) {
;         const int q8 = (wave * 8 + j) * 4 + q;
;         u32x4 nx = {0u, 0u, 0u, 0u};
;         if (tseq0 != 0) nx = *(const GAS u32x4*)((const GAS char*)XAi + pg8::img_chunk(r0 - 16 + rr, q8, KT_D));
; #pragma unroll 1
;         for (int rb = -1; rb < 4; ++rb) {
;             const int row = r0 + rb * 16 + rr;
;             const u32x4 xx = nx;
;             if (rb < 3) nx = *(const GAS u32x4*)((const GAS char*)XAi + pg8::img_chunk(row + 16, q8, KT_D));
;             float v[8];
.LBB0_491:
	s_add_u32 s40, s58, s84
	s_addc_u32 s41, s59, s85
	v_add_u32_e32 v45, 0, v38
	v_add_u32_e32 v44, 0x0, v39
	v_ashrrev_i32_e32 v2, 7, v45
	v_lshrrev_b32_e32 v4, 3, v45
	v_ashrrev_i32_e32 v3, 31, v2
	v_and_or_b32 v4, v4, 14, s46
	v_lshrrev_b32_e32 v5, 4, v44
	v_and_or_b32 v0, v44, s33, v19
	v_lshlrev_b64 v[2:3], 19, v[2:3]
	v_lshlrev_b32_e32 v4, 10, v4
	v_and_b32_e32 v5, 32, v5
	v_bitop3_b32 v0, v4, v0, v5 bitop3:0xf6
	v_lshl_add_u64 v[2:3], s[40:41], 0, v[2:3]
	v_lshl_add_u64 v[2:3], v[2:3], 0, v[0:1]
	global_load_dwordx4 v[64:67], v[2:3], off
	v_add_u32_e32 v45, 16, v38
	v_add_u32_e32 v44, 0x400, v39
	v_ashrrev_i32_e32 v2, 7, v45
	v_lshrrev_b32_e32 v4, 3, v45
	v_ashrrev_i32_e32 v3, 31, v2
	v_and_or_b32 v4, v4, 14, s46
	v_lshrrev_b32_e32 v5, 4, v44
	v_and_or_b32 v0, v44, s33, v19
	v_lshlrev_b64 v[2:3], 19, v[2:3]
	v_lshlrev_b32_e32 v4, 10, v4
	v_and_b32_e32 v5, 32, v5
	v_bitop3_b32 v0, v4, v0, v5 bitop3:0xf6
	v_lshl_add_u64 v[2:3], s[40:41], 0, v[2:3]
	v_lshl_add_u64 v[2:3], v[2:3], 0, v[0:1]
	global_load_dwordx4 v[68:71], v[2:3], off
	v_add_u32_e32 v45, 32, v38
	v_add_u32_e32 v44, 0x800, v39
	v_ashrrev_i32_e32 v2, 7, v45
	v_lshrrev_b32_e32 v4, 3, v45
	v_ashrrev_i32_e32 v3, 31, v2
	v_and_or_b32 v4, v4, 14, s46
	v_lshrrev_b32_e32 v5, 4, v44
	v_and_or_b32 v0, v44, s33, v19
	v_lshlrev_b64 v[2:3], 19, v[2:3]
	v_lshlrev_b32_e32 v4, 10, v4
	v_and_b32_e32 v5, 32, v5
	v_bitop3_b32 v0, v4, v0, v5 bitop3:0xf6
	v_lshl_add_u64 v[2:3], s[40:41], 0, v[2:3]
	v_lshl_add_u64 v[2:3], v[2:3], 0, v[0:1]
	global_load_dwordx4 v[72:75], v[2:3], off
	v_add_u32_e32 v45, 48, v38
	v_add_u32_e32 v44, 0xc00, v39
	v_ashrrev_i32_e32 v2, 7, v45
	v_lshrrev_b32_e32 v4, 3, v45
	v_ashrrev_i32_e32 v3, 31, v2
	v_and_or_b32 v4, v4, 14, s46
	v_lshrrev_b32_e32 v5, 4, v44
	v_and_or_b32 v0, v44, s33, v19
	v_lshlrev_b64 v[2:3], 19, v[2:3]
	v_lshlrev_b32_e32 v4, 10, v4
	v_and_b32_e32 v5, 32, v5
	v_bitop3_b32 v0, v4, v0, v5 bitop3:0xf6
	v_lshl_add_u64 v[2:3], s[40:41], 0, v[2:3]
	v_lshl_add_u64 v[2:3], v[2:3], 0, v[0:1]
	global_load_dwordx4 v[76:79], v[2:3], off
	s_add_u32 s84, s86, s84
	s_waitcnt vmcnt(0)
	v_mov_b64_e32 v[2:3], v[10:11]
	s_addc_u32 s85, s87, s85
	s_mov_b32 s68, -1
	s_mov_b32 s69, 0
	v_mov_b32_e32 v43, v36
	s_mov_b32 s88, 0
	v_mov_b64_e32 v[4:5], v[12:13]
	s_branch .LBB0_493
.LBB0_492:
	s_add_i32 s88, s88, 16
	s_addk_i32 s69, 0x400
	s_add_i32 s68, s68, 1
	v_mov_b64_e32 v[12:13], v[4:5]
	v_add_u32_e32 v43, 64, v43
	s_cmpk_eq_i32 s88, 0x50
	v_mov_b64_e32 v[10:11], v[2:3]
	s_cbranch_scc1 .LBB0_487
.LBB0_493:
	v_add_u32_e32 v45, s88, v38
	s_cmp_eq_u32 s88, 64
	v_add_u32_e32 v44, s69, v39
	s_cbranch_scc1 .LBB0_495
	s_cmp_lg_u32 s88, 0
	s_cbranch_scc1 .Lpool_sel_2_1
	v_mov_b32_e32 v2, v64
	v_mov_b32_e32 v3, v65
	v_mov_b32_e32 v4, v66
	v_mov_b32_e32 v5, v67
	s_branch .LBB0_495
.Lpool_sel_2_1:
	s_cmp_lg_u32 s88, 16
	s_cbranch_scc1 .Lpool_sel_2_2
	v_mov_b32_e32 v2, v68
	v_mov_b32_e32 v3, v69
	v_mov_b32_e32 v4, v70
	v_mov_b32_e32 v5, v71
	s_branch .LBB0_495
.Lpool_sel_2_2:
	s_cmp_lg_u32 s88, 32
	s_cbranch_scc1 .Lpool_sel_2_3
	v_mov_b32_e32 v2, v72
	v_mov_b32_e32 v3, v73
	v_mov_b32_e32 v4, v74
	v_mov_b32_e32 v5, v75
	s_branch .LBB0_495
